# attention tile loops (4 of 7): K-fragment ds_read_b128 ping-pong over two register quads in the QK MFMA chain
# speedup vs baseline: 1.0059x; 1.0059x over previous
; #define LAS __attribute__((address_space(3)))
; #define MFMA32(a, b, c) __builtin_amdgcn_mfma_f32_32x32x16_bf16((a), (b), (c), 0, 0, 0)
;     ...
;             if (BIAS) {
; #pragma unroll
;                 for (int i = 0; i < 16; ++i) { const int c = (i & 3) + 8 * (i >> 2); s0[i] = tb[c * DSC]; s1[i] = tb[(c + 32) * DSC]; }
;             } else {
; #pragma unroll
;                 for (int i = 0; i < 16; ++i) { s0[i] = 0.f; s1[i] = 0.f; }
;             }
; #pragma unroll
;             for (int ks = 0; ks < DK / 16; ++ks) { const bf16x8 ka = *(const LAS bf16x8*)(bb + n * PK + (16 * ks + 8 * h) * 2), kb2 = *(const LAS bf16x8*)(bb + (32 + n) * PK + (16 * ks + 8 * h) * 2);
;                 s0 = MFMA32(ka, qf[ks], s0); s1 = MFMA32(kb2, qf[ks], s1); }
;             const bool interior = (tq_min >= k0 + 63) && (tq_max - k0 < W) && (!SEL || __builtin_amdgcn_ballot_w64(!selok) == 0ull);
.LBB0_130:
	v_lshrrev_b32_e32 v66, s25, v122
	v_and_b32_e32 v66, 1, v66
	v_cmp_eq_u32_e64 s[8:9], 1, v66
	v_bfe_u32 v66, v122, s25, 1
	v_cmp_ne_u32_e32 vcc, 0, v66
	s_cbranch_vccz .LBB0_138
	s_bitcmp1_b32 s25, 0
	s_cselect_b32 s26, 0x4600, 0
	ds_read2_b32 v[66:67], v126 offset1:1
	ds_read2_b32 v[68:69], v126 offset0:2 offset1:3
	ds_read2_b32 v[70:71], v126 offset0:8 offset1:9
	ds_read2_b32 v[72:73], v126 offset0:10 offset1:11
	s_add_i32 s38, s26, 0
	s_add_i32 s38, s38, 0x12000
	v_add3_u32 v128, s38, v177, v181
	ds_read_b128 v[90:93], v128
	ds_read2_b32 v[74:75], v126 offset0:16 offset1:17
	ds_read2_b32 v[76:77], v126 offset0:18 offset1:19
	ds_read2_b32 v[78:79], v126 offset0:24 offset1:25
	ds_read2_b32 v[80:81], v126 offset0:26 offset1:27
	ds_read2_b32 v[82:83], v126 offset0:32 offset1:33
	ds_read2_b32 v[84:85], v126 offset0:34 offset1:35
	ds_read2_b32 v[86:87], v126 offset0:40 offset1:41
	ds_read2_b32 v[88:89], v126 offset0:42 offset1:43
	ds_read_b128 v[146:149], v128 offset:4608
	s_waitcnt lgkmcnt(5)
	v_mfma_f32_32x32x16_bf16 v[66:81], v[90:93], v[130:133], v[66:81]
	ds_read2_b32 v[90:91], v126 offset0:48 offset1:49
	ds_read2_b32 v[92:93], v126 offset0:50 offset1:51
	ds_read2_b32 v[94:95], v126 offset0:56 offset1:57
	ds_read2_b32 v[96:97], v126 offset0:58 offset1:59
	s_add_i32 s26, s30, 0xffffffbf
	s_cmp_lt_i32 s59, s26
	s_cselect_b64 s[26:27], -1, 0
	s_cmp_gt_i32 s31, 0x3fffffff
	s_cselect_b64 s[36:37], -1, 0
	s_or_b64 s[36:37], s[26:27], s[36:37]
	s_waitcnt lgkmcnt(0)
	v_mfma_f32_32x32x16_bf16 v[82:97], v[146:149], v[130:133], v[82:97]
	ds_read_b128 v[146:149], v128 offset:32
	ds_read_b128 v[150:153], v128 offset:4640
	s_and_b64 vcc, exec, s[36:37]
	s_waitcnt lgkmcnt(1)
	v_mfma_f32_32x32x16_bf16 v[66:81], v[146:149], v[134:137], v[66:81]
	ds_read_b128 v[146:149], v128 offset:64
	s_waitcnt lgkmcnt(1)
	v_mfma_f32_32x32x16_bf16 v[82:97], v[150:153], v[134:137], v[82:97]
	ds_read_b128 v[150:153], v128 offset:4672
	s_waitcnt lgkmcnt(1)
	v_mfma_f32_32x32x16_bf16 v[66:81], v[146:149], v[138:141], v[66:81]
	ds_read_b128 v[146:149], v128 offset:96
	s_waitcnt lgkmcnt(1)
	v_mfma_f32_32x32x16_bf16 v[82:97], v[150:153], v[138:141], v[82:97]
	ds_read_b128 v[150:153], v128 offset:4704
	s_waitcnt lgkmcnt(1)
	v_mfma_f32_32x32x16_bf16 v[66:81], v[146:149], v[142:145], v[66:81]
	s_waitcnt lgkmcnt(0)
	v_mfma_f32_32x32x16_bf16 v[82:97], v[150:153], v[142:145], v[82:97]
	s_cbranch_vccnz .LBB0_133
	s_xor_b64 s[26:27], s[8:9], -1
	v_cndmask_b32_e64 v128, 0, 1, s[26:27]
	v_cmp_ne_u32_e32 vcc, 0, v128
	s_cmp_lg_u64 vcc, 0
	s_cselect_b64 s[36:37], -1, 0

; #define LAS __attribute__((address_space(3)))
; #define MFMA32(a, b, c) __builtin_amdgcn_mfma_f32_32x32x16_bf16((a), (b), (c), 0, 0, 0)
;     ...
;         bool work = (kt >= kt_lo && kt <= kt_hi);
;         bool selok = true;
;         if (SEL) { selok = ((selw >> kt) & 1u) != 0u; if (__builtin_amdgcn_ballot_w64(selok) == 0ull) work = false; }
;         if (work) {
;             const LAS unsigned char* bb = tbuf + (kt & 1) * BUF;
;             const int k0 = 64 * kt;
;             const int dbase = tq - k0 - 4 * h;
;             const LAS float* tb = tab - dbase * DSC;
;             f32x16 s0, s1;
;             if (BIAS) {
; #pragma unroll
;                 for (int i = 0; i < 16; ++i) { const int c = (i & 3) + 8 * (i >> 2); s0[i] = tb[c * DSC]; s1[i] = tb[(c + 32) * DSC]; }
;             } else {
; #pragma unroll
;                 for (int i = 0; i < 16; ++i) { s0[i] = 0.f; s1[i] = 0.f; }
;             }
; #pragma unroll
;             for (int ks = 0; ks < DK / 16; ++ks) { const bf16x8 ka = *(const LAS bf16x8*)(bb + n * PK + (16 * ks + 8 * h) * 2), kb2 = *(const LAS bf16x8*)(bb + (32 + n) * PK + (16 * ks + 8 * h) * 2);
;                 s0 = MFMA32(ka, qf[ks], s0); s1 = MFMA32(kb2, qf[ks], s1); }
;             const bool interior = (tq_min >= k0 + 63) && (tq_max - k0 < W) && (!SEL || __builtin_amdgcn_ballot_w64(!selok) == 0ull);
;             if (!interior) {
; #pragma unroll
;                 for (int i = 0; i < 16; ++i) { const int c = (i & 3) + 8 * (i >> 2);
;                     s0[i] = ((unsigned)(dbase - c) < (unsigned)W && selok) ? s0[i] : -INFINITY;
;                     s1[i] = ((unsigned)(dbase - c - 32) < (unsigned)W && selok) ? s1[i] : -INFINITY; }
;             }
.LBB0_314:
	s_cmp_lt_u32 s25, s64
	s_cselect_b64 s[26:27], -1, 0
	s_cmp_gt_i32 s25, s65
	s_cselect_b64 s[36:37], -1, 0
	s_or_b64 s[26:27], s[26:27], s[36:37]
	s_and_b64 vcc, exec, s[26:27]
	s_cbranch_vccnz .LBB0_320
	s_bitcmp1_b32 s25, 0
	s_cselect_b32 s26, 0x4600, 0
	ds_read2_b32 v[34:35], v122 offset0:128 offset1:132
	ds_read2_b32 v[36:37], v122 offset0:136 offset1:140
	ds_read2_b32 v[50:51], v122 offset1:4
	ds_read2_b32 v[52:53], v122 offset0:8 offset1:12
	ds_read2_b32 v[54:55], v122 offset0:32 offset1:36
	ds_read2_b32 v[56:57], v122 offset0:40 offset1:44
	s_add_i32 s36, s26, 0
	s_add_i32 s36, s36, 0x1a000
	v_add3_u32 v123, s36, v110, v118
	ds_read_b128 v[44:47], v123
	ds_read2_b32 v[58:59], v122 offset0:64 offset1:68
	ds_read2_b32 v[60:61], v122 offset0:72 offset1:76
	ds_read2_b32 v[62:63], v122 offset0:96 offset1:100
	ds_read2_b32 v[64:65], v122 offset0:104 offset1:108
	ds_read2_b32 v[38:39], v122 offset0:160 offset1:164
	ds_read2_b32 v[40:41], v122 offset0:168 offset1:172
	ds_read2_b32 v[42:43], v122 offset0:192 offset1:196
	ds_read_b128 v[124:127], v123 offset:4608
	s_waitcnt lgkmcnt(4)
	v_mfma_f32_32x32x16_bf16 v[50:65], v[44:47], v[66:69], v[50:65]
	ds_read2_b32 v[44:45], v122 offset0:200 offset1:204
	ds_read2_b32 v[46:47], v122 offset0:224 offset1:228
	ds_read2_b32 v[48:49], v122 offset0:232 offset1:236
	s_add_i32 s26, s24, 63
	s_cmp_ge_i32 s61, s26
	s_cselect_b64 s[26:27], -1, 0
	s_add_i32 s37, s30, s31
	s_cmpk_lt_i32 s37, 0x81
	s_cselect_b64 s[42:43], -1, 0
	s_waitcnt lgkmcnt(0)
	v_mfma_f32_32x32x16_bf16 v[34:49], v[124:127], v[66:69], v[34:49]
	ds_read_b128 v[124:127], v123 offset:32
	ds_read_b128 v[128:131], v123 offset:4640
	s_and_b64 s[26:27], s[26:27], s[42:43]
	s_and_b64 vcc, exec, s[26:27]
	s_waitcnt lgkmcnt(1)
	v_mfma_f32_32x32x16_bf16 v[50:65], v[124:127], v[70:73], v[50:65]
	ds_read_b128 v[124:127], v123 offset:64
	s_waitcnt lgkmcnt(1)
	v_mfma_f32_32x32x16_bf16 v[34:49], v[128:131], v[70:73], v[34:49]
	ds_read_b128 v[128:131], v123 offset:4672
	s_waitcnt lgkmcnt(1)
	v_mfma_f32_32x32x16_bf16 v[50:65], v[124:127], v[74:77], v[50:65]
	ds_read_b128 v[124:127], v123 offset:96
	s_waitcnt lgkmcnt(1)
	v_mfma_f32_32x32x16_bf16 v[34:49], v[128:131], v[74:77], v[34:49]
	ds_read_b128 v[128:131], v123 offset:4704
	s_waitcnt lgkmcnt(1)
	v_mfma_f32_32x32x16_bf16 v[50:65], v[124:127], v[78:81], v[50:65]
	s_waitcnt lgkmcnt(0)
	v_mfma_f32_32x32x16_bf16 v[34:49], v[128:131], v[78:81], v[34:49]
	s_cbranch_vccnz .LBB0_317
	v_add_u32_e32 v123, s30, v115
	v_cmp_gt_u32_e32 vcc, s2, v123
	v_subrev_u32_e32 v124, 32, v123
	s_nop 5
	v_cndmask_b32_e32 v50, v246, v50, vcc
	v_cmp_gt_u32_e32 vcc, s2, v124
	v_add_u32_e32 v124, -1, v123
	s_nop 0
	v_cndmask_b32_e32 v34, v246, v34, vcc
	v_cmp_gt_u32_e32 vcc, s2, v124
	v_subrev_u32_e32 v124, 33, v123
	s_nop 0
	v_cndmask_b32_e32 v51, v246, v51, vcc
	v_cmp_gt_u32_e32 vcc, s2, v124
	v_add_u32_e32 v124, -2, v123
	s_nop 0
	v_cndmask_b32_e32 v35, v246, v35, vcc
	v_cmp_gt_u32_e32 vcc, s2, v124
	v_subrev_u32_e32 v124, 34, v123
	s_nop 0
	v_cndmask_b32_e32 v52, v246, v52, vcc
	v_cmp_gt_u32_e32 vcc, s2, v124
	v_add_u32_e32 v124, -3, v123
	s_nop 0
	v_cndmask_b32_e32 v36, v246, v36, vcc
	v_cmp_gt_u32_e32 vcc, s2, v124
	v_subrev_u32_e32 v124, 35, v123
	s_nop 0
	v_cndmask_b32_e32 v53, v246, v53, vcc
	v_cmp_gt_u32_e32 vcc, s2, v124
	v_add_u32_e32 v124, -8, v123
	s_nop 0
	v_cndmask_b32_e32 v37, v246, v37, vcc
	v_cmp_gt_u32_e32 vcc, s2, v124
	v_subrev_u32_e32 v124, 40, v123
	s_nop 0
	v_cndmask_b32_e32 v54, v246, v54, vcc
	v_cmp_gt_u32_e32 vcc, s2, v124
	v_add_u32_e32 v124, -9, v123
	s_nop 0
	v_cndmask_b32_e32 v38, v246, v38, vcc
	v_cmp_gt_u32_e32 vcc, s2, v124
	v_subrev_u32_e32 v124, 41, v123
	s_nop 0
	v_cndmask_b32_e32 v55, v246, v55, vcc
	v_cmp_gt_u32_e32 vcc, s2, v124
	v_add_u32_e32 v124, -10, v123
	s_nop 0
	v_cndmask_b32_e32 v39, v246, v39, vcc
	v_cmp_gt_u32_e32 vcc, s2, v124
	v_subrev_u32_e32 v124, 42, v123
	s_nop 0
	v_cndmask_b32_e32 v56, v246, v56, vcc
	v_cmp_gt_u32_e32 vcc, s2, v124
	v_add_u32_e32 v124, -11, v123
	s_nop 0
	v_cndmask_b32_e32 v40, v246, v40, vcc
	v_cmp_gt_u32_e32 vcc, s2, v124
	v_subrev_u32_e32 v124, 43, v123
	s_nop 0
	v_cndmask_b32_e32 v57, v246, v57, vcc
	v_cmp_gt_u32_e32 vcc, s2, v124
	v_add_u32_e32 v124, -16, v123
	s_nop 0
	v_cndmask_b32_e32 v41, v246, v41, vcc
	v_cmp_gt_u32_e32 vcc, s2, v124
	v_subrev_u32_e32 v124, 48, v123
	s_nop 0
	v_cndmask_b32_e32 v58, v246, v58, vcc
	v_cmp_gt_u32_e32 vcc, s2, v124
	v_subrev_u32_e32 v124, 17, v123
	s_nop 0
	v_cndmask_b32_e32 v42, v246, v42, vcc
	v_cmp_gt_u32_e32 vcc, s2, v124
	v_subrev_u32_e32 v124, 49, v123
	s_nop 0
	v_cndmask_b32_e32 v59, v246, v59, vcc
	v_cmp_gt_u32_e32 vcc, s2, v124
	v_subrev_u32_e32 v124, 18, v123
	s_nop 0
	v_cndmask_b32_e32 v43, v246, v43, vcc
	v_cmp_gt_u32_e32 vcc, s2, v124
	v_subrev_u32_e32 v124, 50, v123
	s_nop 0
	v_cndmask_b32_e32 v60, v246, v60, vcc
	v_cmp_gt_u32_e32 vcc, s2, v124
	v_subrev_u32_e32 v124, 19, v123
	s_nop 0
	v_cndmask_b32_e32 v44, v246, v44, vcc
	v_cmp_gt_u32_e32 vcc, s2, v124
	v_subrev_u32_e32 v124, 51, v123
	s_nop 0
	v_cndmask_b32_e32 v61, v246, v61, vcc
	v_cmp_gt_u32_e32 vcc, s2, v124
	v_subrev_u32_e32 v124, 24, v123
	s_nop 0
	v_cndmask_b32_e32 v45, v246, v45, vcc
	v_cmp_gt_u32_e32 vcc, s2, v124
	v_subrev_u32_e32 v124, 56, v123
	s_nop 0
	v_cndmask_b32_e32 v62, v246, v62, vcc
	v_cmp_gt_u32_e32 vcc, s2, v124
	v_subrev_u32_e32 v124, 25, v123
	s_nop 0
	v_cndmask_b32_e32 v46, v246, v46, vcc
	v_cmp_gt_u32_e32 vcc, s2, v124
	v_subrev_u32_e32 v124, 57, v123
	s_nop 0
	v_cndmask_b32_e32 v63, v246, v63, vcc
	v_cmp_gt_u32_e32 vcc, s2, v124
	v_subrev_u32_e32 v124, 26, v123
	s_nop 0
	v_cndmask_b32_e32 v47, v246, v47, vcc
	v_cmp_gt_u32_e32 vcc, s2, v124
	v_subrev_u32_e32 v124, 58, v123
	s_nop 0
	v_cndmask_b32_e32 v64, v246, v64, vcc
	v_cmp_gt_u32_e32 vcc, s2, v124
	v_subrev_u32_e32 v124, 27, v123
	v_subrev_u32_e32 v123, 59, v123
	v_cndmask_b32_e32 v48, v246, v48, vcc
	v_cmp_gt_u32_e32 vcc, s2, v124
	s_nop 1
	v_cndmask_b32_e32 v65, v246, v65, vcc
	v_cmp_gt_u32_e32 vcc, s2, v123
	s_nop 1
	v_cndmask_b32_e32 v49, v246, v49, vcc

; #define LAS __attribute__((address_space(3)))
; #define MFMA32(a, b, c) __builtin_amdgcn_mfma_f32_32x32x16_bf16((a), (b), (c), 0, 0, 0)
;     ...
;         bool work = (kt >= kt_lo && kt <= kt_hi);
;         bool selok = true;
;         if (SEL) { selok = ((selw >> kt) & 1u) != 0u; if (__builtin_amdgcn_ballot_w64(selok) == 0ull) work = false; }
;         if (work) {
;             const LAS unsigned char* bb = tbuf + (kt & 1) * BUF;
;             const int k0 = 64 * kt;
;             const int dbase = tq - k0 - 4 * h;
;             const LAS float* tb = tab - dbase * DSC;
;             f32x16 s0, s1;
;             if (BIAS) {
; #pragma unroll
;                 for (int i = 0; i < 16; ++i) { const int c = (i & 3) + 8 * (i >> 2); s0[i] = tb[c * DSC]; s1[i] = tb[(c + 32) * DSC]; }
;             } else {
; #pragma unroll
;                 for (int i = 0; i < 16; ++i) { s0[i] = 0.f; s1[i] = 0.f; }
;             }
; #pragma unroll
;             for (int ks = 0; ks < DK / 16; ++ks) { const bf16x8 ka = *(const LAS bf16x8*)(bb + n * PK + (16 * ks + 8 * h) * 2), kb2 = *(const LAS bf16x8*)(bb + (32 + n) * PK + (16 * ks + 8 * h) * 2);
;                 s0 = MFMA32(ka, qf[ks], s0); s1 = MFMA32(kb2, qf[ks], s1); }
;             const bool interior = (tq_min >= k0 + 63) && (tq_max - k0 < W) && (!SEL || __builtin_amdgcn_ballot_w64(!selok) == 0ull);
;             if (!interior) {
; #pragma unroll
;                 for (int i = 0; i < 16; ++i) { const int c = (i & 3) + 8 * (i >> 2);
;                     s0[i] = ((unsigned)(dbase - c) < (unsigned)W && selok) ? s0[i] : -INFINITY;
;                     s1[i] = ((unsigned)(dbase - c - 32) < (unsigned)W && selok) ? s1[i] : -INFINITY; }
;             }
.LBB0_328:
	s_cmp_lt_u32 s42, s64
	s_cselect_b64 s[26:27], -1, 0
	s_cmp_gt_i32 s42, s65
	s_cselect_b64 s[48:49], -1, 0
	s_or_b64 s[26:27], s[26:27], s[48:49]
	s_and_b64 vcc, exec, s[26:27]
	s_cbranch_vccnz .LBB0_334
	s_bitcmp1_b32 s42, 0
	s_cselect_b32 s26, 0x4600, 0
	s_add_i32 s43, s26, 0
	v_add_u32_e32 v56, 0x800, v122
	s_add_i32 s43, s43, 0x1a000
	ds_read2_b32 v[34:35], v122 offset1:16
	ds_read2_b32 v[50:51], v56 offset1:16
	ds_read2_b32 v[36:37], v122 offset0:32 offset1:48
	ds_read2_b32 v[52:53], v56 offset0:32 offset1:48
	ds_read2_b32 v[38:39], v122 offset0:128 offset1:144
	ds_read2_b32 v[54:55], v56 offset0:128 offset1:144
	ds_read2_b32 v[40:41], v122 offset0:160 offset1:176
	v_add_u32_e32 v48, 0x400, v122
	v_add3_u32 v123, s43, v110, v118
	ds_read_b128 v[60:63], v123
	ds_read2_b32 v[42:43], v48 offset1:16
	ds_read2_b32 v[44:45], v48 offset0:32 offset1:48
	ds_read2_b32 v[46:47], v48 offset0:128 offset1:144
	ds_read2_b32 v[48:49], v48 offset0:160 offset1:176
	ds_read2_b32 v[56:57], v56 offset0:160 offset1:176
	v_add_u32_e32 v64, 0xc00, v122
	ds_read2_b32 v[58:59], v64 offset1:16
	ds_read_b128 v[124:127], v123 offset:4608
	s_waitcnt lgkmcnt(3)
	v_mfma_f32_32x32x16_bf16 v[34:49], v[60:63], v[66:69], v[34:49]
	ds_read2_b32 v[60:61], v64 offset0:32 offset1:48
	ds_read2_b32 v[62:63], v64 offset0:128 offset1:144
	ds_read2_b32 v[64:65], v64 offset0:160 offset1:176
	s_add_i32 s26, s38, 63
	s_cmp_ge_i32 s61, s26
	s_cselect_b64 s[26:27], -1, 0
	s_add_i32 s45, s30, s31
	s_cmpk_lt_i32 s45, 0x81
	s_cselect_b64 s[48:49], -1, 0
	s_waitcnt lgkmcnt(0)
	v_mfma_f32_32x32x16_bf16 v[50:65], v[124:127], v[66:69], v[50:65]
	ds_read_b128 v[124:127], v123 offset:32
	ds_read_b128 v[128:131], v123 offset:4640
	s_and_b64 s[26:27], s[26:27], s[48:49]
	s_and_b64 vcc, exec, s[26:27]
	s_waitcnt lgkmcnt(1)
	v_mfma_f32_32x32x16_bf16 v[34:49], v[124:127], v[70:73], v[34:49]
	ds_read_b128 v[124:127], v123 offset:64
	s_waitcnt lgkmcnt(1)
	v_mfma_f32_32x32x16_bf16 v[50:65], v[128:131], v[70:73], v[50:65]
	ds_read_b128 v[128:131], v123 offset:4672
	s_waitcnt lgkmcnt(1)
	v_mfma_f32_32x32x16_bf16 v[34:49], v[124:127], v[74:77], v[34:49]
	ds_read_b128 v[124:127], v123 offset:96
	s_waitcnt lgkmcnt(1)
	v_mfma_f32_32x32x16_bf16 v[50:65], v[128:131], v[74:77], v[50:65]
	ds_read_b128 v[128:131], v123 offset:4704
	s_waitcnt lgkmcnt(1)
	v_mfma_f32_32x32x16_bf16 v[34:49], v[124:127], v[78:81], v[34:49]
	s_waitcnt lgkmcnt(0)
	v_mfma_f32_32x32x16_bf16 v[50:65], v[128:131], v[78:81], v[50:65]
	s_cbranch_vccnz .LBB0_331
	v_add_u32_e32 v123, s30, v115
	v_cmp_gt_u32_e32 vcc, s2, v123
	v_subrev_u32_e32 v124, 32, v123
	s_nop 5
	v_cndmask_b32_e32 v34, v246, v34, vcc
	v_cmp_gt_u32_e32 vcc, s2, v124
	v_add_u32_e32 v124, -1, v123
	s_nop 0
	v_cndmask_b32_e32 v50, v246, v50, vcc
	v_cmp_gt_u32_e32 vcc, s2, v124
	v_subrev_u32_e32 v124, 33, v123
	s_nop 0
	v_cndmask_b32_e32 v35, v246, v35, vcc
	v_cmp_gt_u32_e32 vcc, s2, v124
	v_add_u32_e32 v124, -2, v123
	s_nop 0
	v_cndmask_b32_e32 v51, v246, v51, vcc
	v_cmp_gt_u32_e32 vcc, s2, v124
	v_subrev_u32_e32 v124, 34, v123
	s_nop 0
	v_cndmask_b32_e32 v36, v246, v36, vcc
	v_cmp_gt_u32_e32 vcc, s2, v124
	v_add_u32_e32 v124, -3, v123
	s_nop 0
	v_cndmask_b32_e32 v52, v246, v52, vcc
	v_cmp_gt_u32_e32 vcc, s2, v124
	v_subrev_u32_e32 v124, 35, v123
	s_nop 0
	v_cndmask_b32_e32 v37, v246, v37, vcc
	v_cmp_gt_u32_e32 vcc, s2, v124
	v_add_u32_e32 v124, -8, v123
	s_nop 0
	v_cndmask_b32_e32 v53, v246, v53, vcc
	v_cmp_gt_u32_e32 vcc, s2, v124
	v_subrev_u32_e32 v124, 40, v123
	s_nop 0
	v_cndmask_b32_e32 v38, v246, v38, vcc
	v_cmp_gt_u32_e32 vcc, s2, v124
	v_add_u32_e32 v124, -9, v123
	s_nop 0
	v_cndmask_b32_e32 v54, v246, v54, vcc
	v_cmp_gt_u32_e32 vcc, s2, v124
	v_subrev_u32_e32 v124, 41, v123
	s_nop 0
	v_cndmask_b32_e32 v39, v246, v39, vcc
	v_cmp_gt_u32_e32 vcc, s2, v124
	v_add_u32_e32 v124, -10, v123
	s_nop 0
	v_cndmask_b32_e32 v55, v246, v55, vcc
	v_cmp_gt_u32_e32 vcc, s2, v124
	v_subrev_u32_e32 v124, 42, v123
	s_nop 0
	v_cndmask_b32_e32 v40, v246, v40, vcc
	v_cmp_gt_u32_e32 vcc, s2, v124
	v_add_u32_e32 v124, -11, v123
	s_nop 0
	v_cndmask_b32_e32 v56, v246, v56, vcc
	v_cmp_gt_u32_e32 vcc, s2, v124
	v_subrev_u32_e32 v124, 43, v123
	s_nop 0
	v_cndmask_b32_e32 v41, v246, v41, vcc
	v_cmp_gt_u32_e32 vcc, s2, v124
	v_add_u32_e32 v124, -16, v123
	s_nop 0
	v_cndmask_b32_e32 v57, v246, v57, vcc
	v_cmp_gt_u32_e32 vcc, s2, v124
	v_subrev_u32_e32 v124, 48, v123
	s_nop 0
	v_cndmask_b32_e32 v42, v246, v42, vcc
	v_cmp_gt_u32_e32 vcc, s2, v124
	v_subrev_u32_e32 v124, 17, v123
	s_nop 0
	v_cndmask_b32_e32 v58, v246, v58, vcc
	v_cmp_gt_u32_e32 vcc, s2, v124
	v_subrev_u32_e32 v124, 49, v123
	s_nop 0
	v_cndmask_b32_e32 v43, v246, v43, vcc
	v_cmp_gt_u32_e32 vcc, s2, v124
	v_subrev_u32_e32 v124, 18, v123
	s_nop 0
	v_cndmask_b32_e32 v59, v246, v59, vcc
	v_cmp_gt_u32_e32 vcc, s2, v124
	v_subrev_u32_e32 v124, 50, v123
	s_nop 0
	v_cndmask_b32_e32 v44, v246, v44, vcc
	v_cmp_gt_u32_e32 vcc, s2, v124
	v_subrev_u32_e32 v124, 19, v123
	s_nop 0
	v_cndmask_b32_e32 v60, v246, v60, vcc
	v_cmp_gt_u32_e32 vcc, s2, v124
	v_subrev_u32_e32 v124, 51, v123
	s_nop 0
	v_cndmask_b32_e32 v45, v246, v45, vcc
	v_cmp_gt_u32_e32 vcc, s2, v124
	v_subrev_u32_e32 v124, 24, v123
	s_nop 0
	v_cndmask_b32_e32 v61, v246, v61, vcc
	v_cmp_gt_u32_e32 vcc, s2, v124
	v_subrev_u32_e32 v124, 56, v123
	s_nop 0
	v_cndmask_b32_e32 v46, v246, v46, vcc
	v_cmp_gt_u32_e32 vcc, s2, v124
	v_subrev_u32_e32 v124, 25, v123
	s_nop 0
	v_cndmask_b32_e32 v62, v246, v62, vcc
	v_cmp_gt_u32_e32 vcc, s2, v124
	v_subrev_u32_e32 v124, 57, v123
	s_nop 0
	v_cndmask_b32_e32 v47, v246, v47, vcc
	v_cmp_gt_u32_e32 vcc, s2, v124
	v_subrev_u32_e32 v124, 26, v123
	s_nop 0
	v_cndmask_b32_e32 v63, v246, v63, vcc
	v_cmp_gt_u32_e32 vcc, s2, v124
	v_subrev_u32_e32 v124, 58, v123
	s_nop 0
	v_cndmask_b32_e32 v48, v246, v48, vcc
	v_cmp_gt_u32_e32 vcc, s2, v124
	v_subrev_u32_e32 v124, 27, v123
	v_subrev_u32_e32 v123, 59, v123
	v_cndmask_b32_e32 v64, v246, v64, vcc
	v_cmp_gt_u32_e32 vcc, s2, v124
	s_nop 1
	v_cndmask_b32_e32 v49, v246, v49, vcc
	v_cmp_gt_u32_e32 vcc, s2, v123
	s_nop 1
	v_cndmask_b32_e32 v65, v246, v65, vcc

; #define LAS __attribute__((address_space(3)))
; #define MFMA32(a, b, c) __builtin_amdgcn_mfma_f32_32x32x16_bf16((a), (b), (c), 0, 0, 0)
;     ...
;             const LAS unsigned char* bb = tbuf + (kt & 1) * BUF;
;             const int k0 = 64 * kt;
;             const int dbase = tq - k0 - 4 * h;
;             const LAS float* tb = tab - dbase * DSC;
;             f32x16 s0, s1;
;             if (BIAS) {
; #pragma unroll
;                 for (int i = 0; i < 16; ++i) { const int c = (i & 3) + 8 * (i >> 2); s0[i] = tb[c * DSC]; s1[i] = tb[(c + 32) * DSC]; }
;             } else {
; #pragma unroll
;                 for (int i = 0; i < 16; ++i) { s0[i] = 0.f; s1[i] = 0.f; }
;             }
; #pragma unroll
;             for (int ks = 0; ks < DK / 16; ++ks) { const bf16x8 ka = *(const LAS bf16x8*)(bb + n * PK + (16 * ks + 8 * h) * 2), kb2 = *(const LAS bf16x8*)(bb + (32 + n) * PK + (16 * ks + 8 * h) * 2);
;                 s0 = MFMA32(ka, qf[ks], s0); s1 = MFMA32(kb2, qf[ks], s1); }
;             const bool interior = (tq_min >= k0 + 63) && (tq_max - k0 < W) && (!SEL || __builtin_amdgcn_ballot_w64(!selok) == 0ull);
;             if (!interior) {
; #pragma unroll
;                 for (int i = 0; i < 16; ++i) { const int c = (i & 3) + 8 * (i >> 2);
;                     s0[i] = ((unsigned)(dbase - c) < (unsigned)W && selok) ? s0[i] : -INFINITY;
;                     s1[i] = ((unsigned)(dbase - c - 32) < (unsigned)W && selok) ? s1[i] : -INFINITY; }
;             }
.LBB0_348:
	s_cmp_lt_u32 s62, s64
	s_cselect_b64 s[6:7], -1, 0
	s_cmp_gt_i32 s62, s65
	s_cselect_b64 s[14:15], -1, 0
	s_or_b64 s[6:7], s[6:7], s[14:15]
	s_and_b64 vcc, exec, s[6:7]
	s_cbranch_vccnz .LBB0_354
	s_bitcmp1_b32 s62, 0
	s_cselect_b32 s6, 0x4600, 0
	ds_read2_b32 v[34:35], v122 offset1:1
	ds_read2_b32 v[36:37], v122 offset0:2 offset1:3
	ds_read2_b32 v[38:39], v122 offset0:8 offset1:9
	ds_read2_b32 v[40:41], v122 offset0:10 offset1:11
	s_add_i32 s6, s6, 0
	s_add_i32 s6, s6, 0x1a000
	v_add3_u32 v123, s6, v110, v118
	ds_read_b128 v[58:61], v123
	ds_read2_b32 v[42:43], v122 offset0:16 offset1:17
	ds_read2_b32 v[44:45], v122 offset0:18 offset1:19
	ds_read2_b32 v[46:47], v122 offset0:24 offset1:25
	ds_read2_b32 v[48:49], v122 offset0:26 offset1:27
	ds_read2_b32 v[50:51], v122 offset0:32 offset1:33
	ds_read2_b32 v[52:53], v122 offset0:34 offset1:35
	ds_read2_b32 v[54:55], v122 offset0:40 offset1:41
	ds_read2_b32 v[56:57], v122 offset0:42 offset1:43
	ds_read_b128 v[124:127], v123 offset:4608
	s_waitcnt lgkmcnt(5)
	v_mfma_f32_32x32x16_bf16 v[34:49], v[58:61], v[66:69], v[34:49]
	ds_read2_b32 v[58:59], v122 offset0:48 offset1:49
	ds_read2_b32 v[60:61], v122 offset0:50 offset1:51
	ds_read2_b32 v[62:63], v122 offset0:56 offset1:57
	ds_read2_b32 v[64:65], v122 offset0:58 offset1:59
	s_add_i32 s7, s36, 63
	s_cmp_ge_i32 s61, s7
	s_cselect_b64 s[14:15], -1, 0
	s_add_i32 s7, s10, s11
	s_cmpk_lt_i32 s7, 0x81
	s_cselect_b64 s[24:25], -1, 0
	s_waitcnt lgkmcnt(0)
	v_mfma_f32_32x32x16_bf16 v[50:65], v[124:127], v[66:69], v[50:65]
	ds_read_b128 v[124:127], v123 offset:32
	ds_read_b128 v[128:131], v123 offset:4640
	s_and_b64 s[14:15], s[14:15], s[24:25]
	s_and_b64 vcc, exec, s[14:15]
	s_waitcnt lgkmcnt(1)
	v_mfma_f32_32x32x16_bf16 v[34:49], v[124:127], v[70:73], v[34:49]
	ds_read_b128 v[124:127], v123 offset:64
	s_waitcnt lgkmcnt(1)
	v_mfma_f32_32x32x16_bf16 v[50:65], v[128:131], v[70:73], v[50:65]
	ds_read_b128 v[128:131], v123 offset:4672
	s_waitcnt lgkmcnt(1)
	v_mfma_f32_32x32x16_bf16 v[34:49], v[124:127], v[74:77], v[34:49]
	ds_read_b128 v[124:127], v123 offset:96
	s_waitcnt lgkmcnt(1)
	v_mfma_f32_32x32x16_bf16 v[50:65], v[128:131], v[74:77], v[50:65]
	ds_read_b128 v[128:131], v123 offset:4704
	s_waitcnt lgkmcnt(1)
	v_mfma_f32_32x32x16_bf16 v[34:49], v[124:127], v[78:81], v[34:49]
	s_waitcnt lgkmcnt(0)
	v_mfma_f32_32x32x16_bf16 v[50:65], v[128:131], v[78:81], v[50:65]
	s_cbranch_vccnz .LBB0_351
	v_add_u32_e32 v123, s10, v115
	v_cmp_gt_u32_e32 vcc, s2, v123
	v_subrev_u32_e32 v124, 32, v123
	s_nop 5
	v_cndmask_b32_e32 v34, v246, v34, vcc
	v_cmp_gt_u32_e32 vcc, s2, v124
	v_add_u32_e32 v124, -1, v123
	s_nop 0
	v_cndmask_b32_e32 v50, v246, v50, vcc
	v_cmp_gt_u32_e32 vcc, s2, v124
	v_subrev_u32_e32 v124, 33, v123
	s_nop 0
	v_cndmask_b32_e32 v35, v246, v35, vcc
	v_cmp_gt_u32_e32 vcc, s2, v124
	v_add_u32_e32 v124, -2, v123
	s_nop 0
	v_cndmask_b32_e32 v51, v246, v51, vcc
	v_cmp_gt_u32_e32 vcc, s2, v124
	v_subrev_u32_e32 v124, 34, v123
	s_nop 0
	v_cndmask_b32_e32 v36, v246, v36, vcc
	v_cmp_gt_u32_e32 vcc, s2, v124
	v_add_u32_e32 v124, -3, v123
	s_nop 0
	v_cndmask_b32_e32 v52, v246, v52, vcc
	v_cmp_gt_u32_e32 vcc, s2, v124
	v_subrev_u32_e32 v124, 35, v123
	s_nop 0
	v_cndmask_b32_e32 v37, v246, v37, vcc
	v_cmp_gt_u32_e32 vcc, s2, v124
	v_add_u32_e32 v124, -8, v123
	s_nop 0
	v_cndmask_b32_e32 v53, v246, v53, vcc
	v_cmp_gt_u32_e32 vcc, s2, v124
	v_subrev_u32_e32 v124, 40, v123
	s_nop 0
	v_cndmask_b32_e32 v38, v246, v38, vcc
	v_cmp_gt_u32_e32 vcc, s2, v124
	v_add_u32_e32 v124, -9, v123
	s_nop 0
	v_cndmask_b32_e32 v54, v246, v54, vcc
	v_cmp_gt_u32_e32 vcc, s2, v124
	v_subrev_u32_e32 v124, 41, v123
	s_nop 0
	v_cndmask_b32_e32 v39, v246, v39, vcc
	v_cmp_gt_u32_e32 vcc, s2, v124
	v_add_u32_e32 v124, -10, v123
	s_nop 0
	v_cndmask_b32_e32 v55, v246, v55, vcc
	v_cmp_gt_u32_e32 vcc, s2, v124
	v_subrev_u32_e32 v124, 42, v123
	s_nop 0
	v_cndmask_b32_e32 v40, v246, v40, vcc
	v_cmp_gt_u32_e32 vcc, s2, v124
	v_add_u32_e32 v124, -11, v123
	s_nop 0
	v_cndmask_b32_e32 v56, v246, v56, vcc
	v_cmp_gt_u32_e32 vcc, s2, v124
	v_subrev_u32_e32 v124, 43, v123
	s_nop 0
	v_cndmask_b32_e32 v41, v246, v41, vcc
	v_cmp_gt_u32_e32 vcc, s2, v124
	v_add_u32_e32 v124, -16, v123
	s_nop 0
	v_cndmask_b32_e32 v57, v246, v57, vcc
	v_cmp_gt_u32_e32 vcc, s2, v124
	v_subrev_u32_e32 v124, 48, v123
	s_nop 0
	v_cndmask_b32_e32 v42, v246, v42, vcc
	v_cmp_gt_u32_e32 vcc, s2, v124
	v_subrev_u32_e32 v124, 17, v123
	s_nop 0
	v_cndmask_b32_e32 v58, v246, v58, vcc
	v_cmp_gt_u32_e32 vcc, s2, v124
	v_subrev_u32_e32 v124, 49, v123
	s_nop 0
	v_cndmask_b32_e32 v43, v246, v43, vcc
	v_cmp_gt_u32_e32 vcc, s2, v124
	v_subrev_u32_e32 v124, 18, v123
	s_nop 0
	v_cndmask_b32_e32 v59, v246, v59, vcc
	v_cmp_gt_u32_e32 vcc, s2, v124
	v_subrev_u32_e32 v124, 50, v123
	s_nop 0
	v_cndmask_b32_e32 v44, v246, v44, vcc
	v_cmp_gt_u32_e32 vcc, s2, v124
	v_subrev_u32_e32 v124, 19, v123
	s_nop 0
	v_cndmask_b32_e32 v60, v246, v60, vcc
	v_cmp_gt_u32_e32 vcc, s2, v124
	v_subrev_u32_e32 v124, 51, v123
	s_nop 0
	v_cndmask_b32_e32 v45, v246, v45, vcc
	v_cmp_gt_u32_e32 vcc, s2, v124
	v_subrev_u32_e32 v124, 24, v123
	s_nop 0
	v_cndmask_b32_e32 v61, v246, v61, vcc
	v_cmp_gt_u32_e32 vcc, s2, v124
	v_subrev_u32_e32 v124, 56, v123
	s_nop 0
	v_cndmask_b32_e32 v46, v246, v46, vcc
	v_cmp_gt_u32_e32 vcc, s2, v124
	v_subrev_u32_e32 v124, 25, v123
	s_nop 0
	v_cndmask_b32_e32 v62, v246, v62, vcc
	v_cmp_gt_u32_e32 vcc, s2, v124
	v_subrev_u32_e32 v124, 57, v123
	s_nop 0
	v_cndmask_b32_e32 v47, v246, v47, vcc
	v_cmp_gt_u32_e32 vcc, s2, v124
	v_subrev_u32_e32 v124, 26, v123
	s_nop 0
	v_cndmask_b32_e32 v63, v246, v63, vcc
	v_cmp_gt_u32_e32 vcc, s2, v124
	v_subrev_u32_e32 v124, 58, v123
	s_nop 0
	v_cndmask_b32_e32 v48, v246, v48, vcc
	v_cmp_gt_u32_e32 vcc, s2, v124
	v_subrev_u32_e32 v124, 27, v123
	v_subrev_u32_e32 v123, 59, v123
	v_cndmask_b32_e32 v64, v246, v64, vcc
	v_cmp_gt_u32_e32 vcc, s2, v124
	s_nop 1
	v_cndmask_b32_e32 v49, v246, v49, vcc
	v_cmp_gt_u32_e32 vcc, s2, v123
	s_nop 1
	v_cndmask_b32_e32 v65, v246, v65, vcc
